# grid-barrier poll back-off: s_sleep 1 -> s_sleep 3 between polls
# speedup vs baseline: 1.0019x; 1.0019x over previous
; __device__ __forceinline__ int otid() { int t = threadIdx.x; asm volatile("" : "+v"(t)); return t; }
; __device__ __forceinline__ unsigned xb_add(unsigned* p, unsigned v) { return __hip_atomic_fetch_add(p, v, __ATOMIC_RELAXED, __HIP_MEMORY_SCOPE_AGENT); }
; __device__ __forceinline__ unsigned xb_xcc_id() { return (unsigned)__builtin_amdgcn_s_getreg((3 << 11) | 20) & 0xFu; }
; __global__ void __launch_bounds__(512, 2) mega(Params p) {
;     ...
;   if (otid() == 0) { const unsigned x = xb_xcc_id(); bst[0] = x; bst[3] = xb_add((unsigned*)((unsigned char*)karg(15) + WS_BAR) + XB_XCNT(x), 1u); }
;   grid.sync();
.LBB0_10:
	s_sleep 3
	global_load_dword v2, v0, s[6:7] offset:32 sc1
	s_waitcnt vmcnt(0)
	v_and_b32_e32 v2, 0xffff0000, v2
	v_cmp_ne_u32_e32 vcc, v2, v1
	s_or_b64 s[8:9], vcc, s[8:9]
	s_andn2_b64 exec, exec, s[8:9]
	s_cbranch_execnz .LBB0_10

; __device__ __forceinline__ unsigned xb_ld(unsigned* p) { return __hip_atomic_load(p, __ATOMIC_RELAXED, __HIP_MEMORY_SCOPE_AGENT); }
; __device__ __forceinline__ void gbar(unsigned* bar, unsigned n, volatile LAS unsigned* st) {
;     ...
;     } else {
;       while (xb_ld(&bar[XB_XGEN(x)]) <= n) { __builtin_amdgcn_s_sleep(1); if (++sp > (1u << 24)) break; }
;       __builtin_amdgcn_fence(__ATOMIC_ACQUIRE, "agent");
.LBB0_111:
	global_load_dword v2, v[0:1], off sc1
	s_or_b64 s[36:37], s[36:37], exec
	s_waitcnt vmcnt(0) lgkmcnt(0)
	v_cmp_le_u32_e32 vcc, v2, v236
	s_and_saveexec_b64 s[38:39], vcc
	s_cbranch_execz .LBB0_110
	s_cmp_lg_u32 s13, 0
	s_sleep 3
	s_cbranch_scc0 .LBB0_121
	global_load_dword v2, v[0:1], off sc1
	s_mov_b64 s[18:19], -1
	s_waitcnt vmcnt(0) lgkmcnt(0)
	v_cmp_le_u32_e32 vcc, v2, v236
	s_and_saveexec_b64 s[40:41], vcc
	s_cbranch_execz .LBB0_108
	s_sleep 3
	global_load_dword v2, v[0:1], off sc1
	s_waitcnt vmcnt(0) lgkmcnt(0)
	v_cmp_le_u32_e32 vcc, v2, v236
	s_and_saveexec_b64 s[42:43], vcc
	s_cbranch_execz .LBB0_107
	s_sleep 3
	global_load_dword v2, v[0:1], off sc1
	s_waitcnt vmcnt(0) lgkmcnt(0)
	v_cmp_le_u32_e32 vcc, v2, v236
	s_and_saveexec_b64 s[44:45], vcc
	s_cbranch_execz .LBB0_106
	s_sleep 3
	global_load_dword v2, v[0:1], off sc1
	s_waitcnt vmcnt(0) lgkmcnt(0)
	v_cmp_le_u32_e32 vcc, v2, v236
	s_and_saveexec_b64 s[46:47], vcc
	s_cbranch_execz .LBB0_105
	s_sleep 3
	global_load_dword v2, v[0:1], off sc1
	s_waitcnt vmcnt(0) lgkmcnt(0)
	v_cmp_le_u32_e32 vcc, v2, v236
	s_and_saveexec_b64 s[68:69], vcc
	s_cbranch_execz .LBB0_104
	s_sleep 3
	global_load_dword v2, v[0:1], off sc1
	s_mov_b64 s[90:91], -1
	s_waitcnt vmcnt(0) lgkmcnt(0)
	v_cmp_le_u32_e32 vcc, v2, v236
	s_and_saveexec_b64 s[18:19], vcc
	s_cbranch_execz .LBB0_103
	s_sleep 3
	global_load_dword v2, v[0:1], off sc1
	s_mov_b64 s[48:49], -1
	s_waitcnt vmcnt(0) lgkmcnt(0)
	v_cmp_le_u32_e32 vcc, v2, v236
	s_and_saveexec_b64 s[90:91], vcc
	s_cbranch_execz .LBB0_102
	s_add_i32 s13, s13, -8
	s_xor_b64 s[48:49], exec, -1
	s_sleep 3
	s_branch .LBB0_102

; __device__ __forceinline__ unsigned xb_ld(unsigned* p) { return __hip_atomic_load(p, __ATOMIC_RELAXED, __HIP_MEMORY_SCOPE_AGENT); }
; __device__ __forceinline__ unsigned xb_add(unsigned* p, unsigned v) { return __hip_atomic_fetch_add(p, v, __ATOMIC_RELAXED, __HIP_MEMORY_SCOPE_AGENT); }
; __device__ __forceinline__ void gbar(unsigned* bar, unsigned n, volatile LAS unsigned* st) {
;     ...
;       xb_add(&bar[XB_TOP], 1u);
;       while (xb_ld(&bar[XB_TOP]) < (n + 1u) * nx) { __builtin_amdgcn_s_sleep(1); if (++sp > (1u << 24)) break; }
;       __builtin_amdgcn_fence(__ATOMIC_ACQUIRE, "agent");
.LBB0_134:
	v_mov_b64_e32 v[2:3], s[8:9]
	global_load_dword v1, v[2:3], off sc1
	s_or_b64 s[38:39], s[38:39], exec
	s_waitcnt vmcnt(0) lgkmcnt(0)
	v_cmp_lt_u32_e32 vcc, v1, v0
	s_and_saveexec_b64 s[40:41], vcc
	s_cbranch_execz .LBB0_133
	s_cmp_lg_u32 s0, 0
	s_sleep 3
	s_cbranch_scc0 .LBB0_144
	v_mov_b64_e32 v[2:3], s[8:9]
	global_load_dword v1, v[2:3], off sc1
	s_mov_b64 s[18:19], -1
	s_waitcnt vmcnt(0) lgkmcnt(0)
	v_cmp_lt_u32_e32 vcc, v1, v0
	s_and_saveexec_b64 s[42:43], vcc
	s_cbranch_execz .LBB0_131
	v_mov_b64_e32 v[2:3], s[8:9]
	s_sleep 3
	global_load_dword v1, v[2:3], off sc1
	s_waitcnt vmcnt(0) lgkmcnt(0)
	v_cmp_lt_u32_e32 vcc, v1, v0
	s_and_saveexec_b64 s[44:45], vcc
	s_cbranch_execz .LBB0_130
	v_mov_b64_e32 v[2:3], s[8:9]
	s_sleep 3
	global_load_dword v1, v[2:3], off sc1
	s_waitcnt vmcnt(0) lgkmcnt(0)
	v_cmp_lt_u32_e32 vcc, v1, v0
	s_and_saveexec_b64 s[46:47], vcc
	s_cbranch_execz .LBB0_129
	v_mov_b64_e32 v[2:3], s[8:9]
	s_sleep 3
	global_load_dword v1, v[2:3], off sc1
	s_waitcnt vmcnt(0) lgkmcnt(0)
	v_cmp_lt_u32_e32 vcc, v1, v0
	s_and_saveexec_b64 s[68:69], vcc
	s_cbranch_execz .LBB0_128
	v_mov_b64_e32 v[2:3], s[8:9]
	s_sleep 3
	global_load_dword v1, v[2:3], off sc1
	s_waitcnt vmcnt(0) lgkmcnt(0)
	v_cmp_lt_u32_e32 vcc, v1, v0
	s_and_saveexec_b64 s[90:91], vcc
	s_cbranch_execz .LBB0_127
	v_mov_b64_e32 v[2:3], s[8:9]
	s_sleep 3
	global_load_dword v1, v[2:3], off sc1
	s_waitcnt vmcnt(0) lgkmcnt(0)
	v_cmp_lt_u32_e32 vcc, v1, v0
	s_and_saveexec_b64 s[94:95], vcc
	s_cbranch_execz .LBB0_126
	v_mov_b64_e32 v[2:3], s[8:9]
	s_sleep 3
	global_load_dword v1, v[2:3], off sc1
	s_waitcnt vmcnt(0) lgkmcnt(0)
	v_cmp_lt_u32_e32 vcc, v1, v0
	s_and_saveexec_b64 s[48:49], vcc
	s_cbranch_execz .LBB0_125
	s_add_i32 s0, s0, -8
	s_xor_b64 s[18:19], exec, -1
	s_sleep 3
	s_branch .LBB0_125

; __device__ __forceinline__ unsigned xb_ld(unsigned* p) { return __hip_atomic_load(p, __ATOMIC_RELAXED, __HIP_MEMORY_SCOPE_AGENT); }
; __device__ __forceinline__ void gbar(unsigned* bar, unsigned n, volatile LAS unsigned* st) {
;     ...
;     } else {
;       while (xb_ld(&bar[XB_XGEN(x)]) <= n) { __builtin_amdgcn_s_sleep(1); if (++sp > (1u << 24)) break; }
;       __builtin_amdgcn_fence(__ATOMIC_ACQUIRE, "agent");
.LBB0_181:
	global_load_dword v2, v[0:1], off sc1
	s_or_b64 s[36:37], s[36:37], exec
	s_waitcnt vmcnt(0) lgkmcnt(0)
	v_cmp_le_u32_e32 vcc, v2, v162
	s_and_saveexec_b64 s[38:39], vcc
	s_cbranch_execz .LBB0_180
	s_cmp_lg_u32 s13, 0
	s_sleep 3
	s_cbranch_scc0 .LBB0_191
	global_load_dword v2, v[0:1], off sc1
	s_mov_b64 s[18:19], -1
	s_waitcnt vmcnt(0) lgkmcnt(0)
	v_cmp_le_u32_e32 vcc, v2, v162
	s_and_saveexec_b64 s[40:41], vcc
	s_cbranch_execz .LBB0_178
	s_sleep 3
	global_load_dword v2, v[0:1], off sc1
	s_waitcnt vmcnt(0) lgkmcnt(0)
	v_cmp_le_u32_e32 vcc, v2, v162
	s_and_saveexec_b64 s[42:43], vcc
	s_cbranch_execz .LBB0_177
	s_sleep 3
	global_load_dword v2, v[0:1], off sc1
	s_waitcnt vmcnt(0) lgkmcnt(0)
	v_cmp_le_u32_e32 vcc, v2, v162
	s_and_saveexec_b64 s[44:45], vcc
	s_cbranch_execz .LBB0_176
	s_sleep 3
	global_load_dword v2, v[0:1], off sc1
	s_waitcnt vmcnt(0) lgkmcnt(0)
	v_cmp_le_u32_e32 vcc, v2, v162
	s_and_saveexec_b64 s[46:47], vcc
	s_cbranch_execz .LBB0_175
	s_sleep 3
	global_load_dword v2, v[0:1], off sc1
	s_waitcnt vmcnt(0) lgkmcnt(0)
	v_cmp_le_u32_e32 vcc, v2, v162
	s_and_saveexec_b64 s[68:69], vcc
	s_cbranch_execz .LBB0_174
	s_sleep 3
	global_load_dword v2, v[0:1], off sc1
	s_mov_b64 s[48:49], -1
	s_waitcnt vmcnt(0) lgkmcnt(0)
	v_cmp_le_u32_e32 vcc, v2, v162
	s_and_saveexec_b64 s[18:19], vcc
	s_cbranch_execz .LBB0_173
	s_sleep 3
	global_load_dword v2, v[0:1], off sc1
	s_waitcnt vmcnt(0) lgkmcnt(0)
	v_cmp_le_u32_e32 vcc, v2, v162
	s_and_saveexec_b64 s[66:67], vcc
	s_cbranch_execz .LBB0_172
	s_add_i32 s13, s13, -8
	s_xor_b64 s[48:49], exec, -1
	s_sleep 3
	s_branch .LBB0_172

; __device__ __forceinline__ unsigned xb_ld(unsigned* p) { return __hip_atomic_load(p, __ATOMIC_RELAXED, __HIP_MEMORY_SCOPE_AGENT); }
; __device__ __forceinline__ unsigned xb_add(unsigned* p, unsigned v) { return __hip_atomic_fetch_add(p, v, __ATOMIC_RELAXED, __HIP_MEMORY_SCOPE_AGENT); }
; __device__ __forceinline__ void gbar(unsigned* bar, unsigned n, volatile LAS unsigned* st) {
;     ...
;       xb_add(&bar[XB_TOP], 1u);
;       while (xb_ld(&bar[XB_TOP]) < (n + 1u) * nx) { __builtin_amdgcn_s_sleep(1); if (++sp > (1u << 24)) break; }
;       __builtin_amdgcn_fence(__ATOMIC_ACQUIRE, "agent");
.LBB0_204:
	v_mov_b64_e32 v[2:3], s[8:9]
	global_load_dword v2, v[2:3], off sc1
	s_or_b64 s[38:39], s[38:39], exec
	s_waitcnt vmcnt(0) lgkmcnt(0)
	v_cmp_lt_u32_e32 vcc, v2, v1
	s_and_saveexec_b64 s[40:41], vcc
	s_cbranch_execz .LBB0_203
	s_cmp_lg_u32 s0, 0
	s_sleep 3
	s_cbranch_scc0 .LBB0_214
	v_mov_b64_e32 v[2:3], s[8:9]
	global_load_dword v2, v[2:3], off sc1
	s_mov_b64 s[18:19], -1
	s_waitcnt vmcnt(0) lgkmcnt(0)
	v_cmp_lt_u32_e32 vcc, v2, v1
	s_and_saveexec_b64 s[42:43], vcc
	s_cbranch_execz .LBB0_201
	v_mov_b64_e32 v[2:3], s[8:9]
	s_sleep 3
	global_load_dword v2, v[2:3], off sc1
	s_waitcnt vmcnt(0) lgkmcnt(0)
	v_cmp_lt_u32_e32 vcc, v2, v1
	s_and_saveexec_b64 s[44:45], vcc
	s_cbranch_execz .LBB0_200
	v_mov_b64_e32 v[2:3], s[8:9]
	s_sleep 3
	global_load_dword v2, v[2:3], off sc1
	s_waitcnt vmcnt(0) lgkmcnt(0)
	v_cmp_lt_u32_e32 vcc, v2, v1
	s_and_saveexec_b64 s[46:47], vcc
	s_cbranch_execz .LBB0_199
	v_mov_b64_e32 v[2:3], s[8:9]
	s_sleep 3
	global_load_dword v2, v[2:3], off sc1
	s_waitcnt vmcnt(0) lgkmcnt(0)
	v_cmp_lt_u32_e32 vcc, v2, v1
	s_and_saveexec_b64 s[68:69], vcc
	s_cbranch_execz .LBB0_198
	v_mov_b64_e32 v[2:3], s[8:9]
	s_sleep 3
	global_load_dword v2, v[2:3], off sc1
	s_waitcnt vmcnt(0) lgkmcnt(0)
	v_cmp_lt_u32_e32 vcc, v2, v1
	s_and_saveexec_b64 s[94:95], vcc
	s_cbranch_execz .LBB0_197
	v_mov_b64_e32 v[2:3], s[8:9]
	s_sleep 3
	global_load_dword v2, v[2:3], off sc1
	s_mov_b64 s[48:49], -1
	s_waitcnt vmcnt(0) lgkmcnt(0)
	v_cmp_lt_u32_e32 vcc, v2, v1
	s_and_saveexec_b64 s[18:19], vcc
	s_cbranch_execz .LBB0_196
	v_mov_b64_e32 v[2:3], s[8:9]
	s_sleep 3
	global_load_dword v2, v[2:3], off sc1
	s_waitcnt vmcnt(0) lgkmcnt(0)
	v_cmp_lt_u32_e32 vcc, v2, v1
	s_and_saveexec_b64 s[66:67], vcc
	s_cbranch_execz .LBB0_195
	s_add_i32 s0, s0, -8
	s_xor_b64 s[48:49], exec, -1
	s_sleep 3
	s_branch .LBB0_195

; __device__ __forceinline__ unsigned xb_ld(unsigned* p) { return __hip_atomic_load(p, __ATOMIC_RELAXED, __HIP_MEMORY_SCOPE_AGENT); }
; __device__ __forceinline__ void gbar(unsigned* bar, unsigned n, volatile LAS unsigned* st) {
;     ...
;     } else {
;       while (xb_ld(&bar[XB_XGEN(x)]) <= n) { __builtin_amdgcn_s_sleep(1); if (++sp > (1u << 24)) break; }
;       __builtin_amdgcn_fence(__ATOMIC_ACQUIRE, "agent");
.LBB0_283:
	global_load_dword v2, v[0:1], off sc1
	s_or_b64 s[38:39], s[38:39], exec
	s_waitcnt vmcnt(0) lgkmcnt(0)
	v_cmp_le_u32_e32 vcc, v2, v158
	s_and_saveexec_b64 s[40:41], vcc
	s_cbranch_execz .LBB0_282
	s_cmp_lg_u32 s13, 0
	s_sleep 3
	s_cbranch_scc0 .LBB0_293
	global_load_dword v2, v[0:1], off sc1
	s_mov_b64 s[18:19], -1
	s_waitcnt vmcnt(0) lgkmcnt(0)
	v_cmp_le_u32_e32 vcc, v2, v158
	s_and_saveexec_b64 s[42:43], vcc
	s_cbranch_execz .LBB0_280
	s_sleep 3
	global_load_dword v2, v[0:1], off sc1
	s_waitcnt vmcnt(0) lgkmcnt(0)
	v_cmp_le_u32_e32 vcc, v2, v158
	s_and_saveexec_b64 s[44:45], vcc
	s_cbranch_execz .LBB0_279
	s_sleep 3
	global_load_dword v2, v[0:1], off sc1
	s_waitcnt vmcnt(0) lgkmcnt(0)
	v_cmp_le_u32_e32 vcc, v2, v158
	s_and_saveexec_b64 s[46:47], vcc
	s_cbranch_execz .LBB0_278
	s_sleep 3
	global_load_dword v2, v[0:1], off sc1
	s_waitcnt vmcnt(0) lgkmcnt(0)
	v_cmp_le_u32_e32 vcc, v2, v158
	s_and_saveexec_b64 s[68:69], vcc
	s_cbranch_execz .LBB0_277
	s_sleep 3
	global_load_dword v2, v[0:1], off sc1
	s_waitcnt vmcnt(0) lgkmcnt(0)
	v_cmp_le_u32_e32 vcc, v2, v158
	s_and_saveexec_b64 s[94:95], vcc
	s_cbranch_execz .LBB0_276
	s_sleep 3
	global_load_dword v2, v[0:1], off sc1
	s_mov_b64 s[48:49], -1
	s_waitcnt vmcnt(0) lgkmcnt(0)
	v_cmp_le_u32_e32 vcc, v2, v158
	s_and_saveexec_b64 s[18:19], vcc
	s_cbranch_execz .LBB0_275
	s_sleep 3
	global_load_dword v2, v[0:1], off sc1
	s_waitcnt vmcnt(0) lgkmcnt(0)
	v_cmp_le_u32_e32 vcc, v2, v158
	s_and_saveexec_b64 s[66:67], vcc
	s_cbranch_execz .LBB0_274
	s_add_i32 s13, s13, -8
	s_xor_b64 s[48:49], exec, -1
	s_sleep 3
	s_branch .LBB0_274

; __device__ __forceinline__ unsigned xb_ld(unsigned* p) { return __hip_atomic_load(p, __ATOMIC_RELAXED, __HIP_MEMORY_SCOPE_AGENT); }
; __device__ __forceinline__ unsigned xb_add(unsigned* p, unsigned v) { return __hip_atomic_fetch_add(p, v, __ATOMIC_RELAXED, __HIP_MEMORY_SCOPE_AGENT); }
; __device__ __forceinline__ void gbar(unsigned* bar, unsigned n, volatile LAS unsigned* st) {
;     ...
;       xb_add(&bar[XB_TOP], 1u);
;       while (xb_ld(&bar[XB_TOP]) < (n + 1u) * nx) { __builtin_amdgcn_s_sleep(1); if (++sp > (1u << 24)) break; }
;       __builtin_amdgcn_fence(__ATOMIC_ACQUIRE, "agent");
.LBB0_306:
	v_mov_b64_e32 v[2:3], s[8:9]
	global_load_dword v1, v[2:3], off sc1
	s_or_b64 s[40:41], s[40:41], exec
	s_waitcnt vmcnt(0) lgkmcnt(0)
	v_cmp_lt_u32_e32 vcc, v1, v0
	s_and_saveexec_b64 s[42:43], vcc
	s_cbranch_execz .LBB0_305
	s_cmp_lg_u32 s0, 0
	s_sleep 3
	s_cbranch_scc0 .LBB0_316
	v_mov_b64_e32 v[2:3], s[8:9]
	global_load_dword v1, v[2:3], off sc1
	s_mov_b64 s[18:19], -1
	s_waitcnt vmcnt(0) lgkmcnt(0)
	v_cmp_lt_u32_e32 vcc, v1, v0
	s_and_saveexec_b64 s[44:45], vcc
	s_cbranch_execz .LBB0_303
	v_mov_b64_e32 v[2:3], s[8:9]
	s_sleep 3
	global_load_dword v1, v[2:3], off sc1
	s_waitcnt vmcnt(0) lgkmcnt(0)
	v_cmp_lt_u32_e32 vcc, v1, v0
	s_and_saveexec_b64 s[68:69], vcc
	s_cbranch_execz .LBB0_302
	v_mov_b64_e32 v[2:3], s[8:9]
	s_sleep 3
	global_load_dword v1, v[2:3], off sc1
	s_waitcnt vmcnt(0) lgkmcnt(0)
	v_cmp_lt_u32_e32 vcc, v1, v0
	s_and_saveexec_b64 s[46:47], vcc
	s_cbranch_execz .LBB0_301
	v_mov_b64_e32 v[2:3], s[8:9]
	s_sleep 3
	global_load_dword v1, v[2:3], off sc1
	s_waitcnt vmcnt(0) lgkmcnt(0)
	v_cmp_lt_u32_e32 vcc, v1, v0
	s_and_saveexec_b64 s[94:95], vcc
	s_cbranch_execz .LBB0_300
	v_mov_b64_e32 v[2:3], s[8:9]
	s_sleep 3
	global_load_dword v1, v[2:3], off sc1
	s_waitcnt vmcnt(0) lgkmcnt(0)
	v_cmp_lt_u32_e32 vcc, v1, v0
	s_and_saveexec_b64 s[96:97], vcc
	s_cbranch_execz .LBB0_299
	v_mov_b64_e32 v[2:3], s[8:9]
	s_sleep 3
	global_load_dword v1, v[2:3], off sc1
	s_mov_b64 s[48:49], -1
	s_waitcnt vmcnt(0) lgkmcnt(0)
	v_cmp_lt_u32_e32 vcc, v1, v0
	s_and_saveexec_b64 s[18:19], vcc
	s_cbranch_execz .LBB0_298
	v_mov_b64_e32 v[2:3], s[8:9]
	s_sleep 3
	global_load_dword v1, v[2:3], off sc1
	s_waitcnt vmcnt(0) lgkmcnt(0)
	v_cmp_lt_u32_e32 vcc, v1, v0
	s_and_saveexec_b64 s[66:67], vcc
	s_cbranch_execz .LBB0_297
	s_add_i32 s0, s0, -8
	s_xor_b64 s[48:49], exec, -1
	s_sleep 3
	s_branch .LBB0_297

; __device__ __forceinline__ unsigned xb_ld(unsigned* p) { return __hip_atomic_load(p, __ATOMIC_RELAXED, __HIP_MEMORY_SCOPE_AGENT); }
; __device__ __forceinline__ void gbar(unsigned* bar, unsigned n, volatile LAS unsigned* st) {
;     ...
;     } else {
;       while (xb_ld(&bar[XB_XGEN(x)]) <= n) { __builtin_amdgcn_s_sleep(1); if (++sp > (1u << 24)) break; }
;       __builtin_amdgcn_fence(__ATOMIC_ACQUIRE, "agent");
.LBB0_355:
	global_load_dword v2, v[0:1], off sc1
	s_or_b64 s[36:37], s[36:37], exec
	s_waitcnt vmcnt(0) lgkmcnt(0)
	v_cmp_le_u32_e32 vcc, v2, v56
	s_and_saveexec_b64 s[38:39], vcc
	s_cbranch_execz .LBB0_354
	s_cmp_lg_u32 s29, 0
	s_sleep 3
	s_cbranch_scc0 .LBB0_365
	global_load_dword v2, v[0:1], off sc1
	s_mov_b64 s[18:19], -1
	s_waitcnt vmcnt(0) lgkmcnt(0)
	v_cmp_le_u32_e32 vcc, v2, v56
	s_and_saveexec_b64 s[42:43], vcc
	s_cbranch_execz .LBB0_352
	s_sleep 3
	global_load_dword v2, v[0:1], off sc1
	s_waitcnt vmcnt(0) lgkmcnt(0)
	v_cmp_le_u32_e32 vcc, v2, v56
	s_and_saveexec_b64 s[44:45], vcc
	s_cbranch_execz .LBB0_351
	s_sleep 3
	global_load_dword v2, v[0:1], off sc1
	s_waitcnt vmcnt(0) lgkmcnt(0)
	v_cmp_le_u32_e32 vcc, v2, v56
	s_and_saveexec_b64 s[46:47], vcc
	s_cbranch_execz .LBB0_350
	s_sleep 3
	global_load_dword v2, v[0:1], off sc1
	s_waitcnt vmcnt(0) lgkmcnt(0)
	v_cmp_le_u32_e32 vcc, v2, v56
	s_and_saveexec_b64 s[68:69], vcc
	s_cbranch_execz .LBB0_349
	s_sleep 3
	global_load_dword v2, v[0:1], off sc1
	s_waitcnt vmcnt(0) lgkmcnt(0)
	v_cmp_le_u32_e32 vcc, v2, v56
	s_and_saveexec_b64 s[94:95], vcc
	s_cbranch_execz .LBB0_348
	s_sleep 3
	global_load_dword v2, v[0:1], off sc1
	s_mov_b64 s[48:49], -1
	s_waitcnt vmcnt(0) lgkmcnt(0)
	v_cmp_le_u32_e32 vcc, v2, v56
	s_and_saveexec_b64 s[18:19], vcc
	s_cbranch_execz .LBB0_347
	s_sleep 3
	global_load_dword v2, v[0:1], off sc1
	s_waitcnt vmcnt(0) lgkmcnt(0)
	v_cmp_le_u32_e32 vcc, v2, v56
	s_and_saveexec_b64 s[66:67], vcc
	s_cbranch_execz .LBB0_346
	s_add_i32 s29, s29, -8
	s_xor_b64 s[48:49], exec, -1
	s_sleep 3
	s_branch .LBB0_346

; __device__ __forceinline__ unsigned xb_ld(unsigned* p) { return __hip_atomic_load(p, __ATOMIC_RELAXED, __HIP_MEMORY_SCOPE_AGENT); }
; __device__ __forceinline__ unsigned xb_add(unsigned* p, unsigned v) { return __hip_atomic_fetch_add(p, v, __ATOMIC_RELAXED, __HIP_MEMORY_SCOPE_AGENT); }
; __device__ __forceinline__ void gbar(unsigned* bar, unsigned n, volatile LAS unsigned* st) {
;     ...
;       xb_add(&bar[XB_TOP], 1u);
;       while (xb_ld(&bar[XB_TOP]) < (n + 1u) * nx) { __builtin_amdgcn_s_sleep(1); if (++sp > (1u << 24)) break; }
;       __builtin_amdgcn_fence(__ATOMIC_ACQUIRE, "agent");
.LBB0_378:
	v_mov_b64_e32 v[2:3], s[8:9]
	global_load_dword v1, v[2:3], off sc1
	s_or_b64 s[38:39], s[38:39], exec
	s_waitcnt vmcnt(0) lgkmcnt(0)
	v_cmp_lt_u32_e32 vcc, v1, v0
	s_and_saveexec_b64 s[42:43], vcc
	s_cbranch_execz .LBB0_377
	s_cmp_lg_u32 s0, 0
	s_sleep 3
	s_cbranch_scc0 .LBB0_388
	v_mov_b64_e32 v[2:3], s[8:9]
	global_load_dword v1, v[2:3], off sc1
	s_mov_b64 s[18:19], -1
	s_waitcnt vmcnt(0) lgkmcnt(0)
	v_cmp_lt_u32_e32 vcc, v1, v0
	s_and_saveexec_b64 s[44:45], vcc
	s_cbranch_execz .LBB0_375
	v_mov_b64_e32 v[2:3], s[8:9]
	s_sleep 3
	global_load_dword v1, v[2:3], off sc1
	s_waitcnt vmcnt(0) lgkmcnt(0)
	v_cmp_lt_u32_e32 vcc, v1, v0
	s_and_saveexec_b64 s[68:69], vcc
	s_cbranch_execz .LBB0_374
	v_mov_b64_e32 v[2:3], s[8:9]
	s_sleep 3
	global_load_dword v1, v[2:3], off sc1
	s_waitcnt vmcnt(0) lgkmcnt(0)
	v_cmp_lt_u32_e32 vcc, v1, v0
	s_and_saveexec_b64 s[46:47], vcc
	s_cbranch_execz .LBB0_373
	v_mov_b64_e32 v[2:3], s[8:9]
	s_sleep 3
	global_load_dword v1, v[2:3], off sc1
	s_waitcnt vmcnt(0) lgkmcnt(0)
	v_cmp_lt_u32_e32 vcc, v1, v0
	s_and_saveexec_b64 s[94:95], vcc
	s_cbranch_execz .LBB0_372
	v_mov_b64_e32 v[2:3], s[8:9]
	s_sleep 3
	global_load_dword v1, v[2:3], off sc1
	s_waitcnt vmcnt(0) lgkmcnt(0)
	v_cmp_lt_u32_e32 vcc, v1, v0
	s_and_saveexec_b64 s[96:97], vcc
	s_cbranch_execz .LBB0_371
	v_mov_b64_e32 v[2:3], s[8:9]
	s_sleep 3
	global_load_dword v1, v[2:3], off sc1
	s_mov_b64 s[48:49], -1
	s_waitcnt vmcnt(0) lgkmcnt(0)
	v_cmp_lt_u32_e32 vcc, v1, v0
	s_and_saveexec_b64 s[18:19], vcc
	s_cbranch_execz .LBB0_370
	v_mov_b64_e32 v[2:3], s[8:9]
	s_sleep 3
	global_load_dword v1, v[2:3], off sc1
	s_waitcnt vmcnt(0) lgkmcnt(0)
	v_cmp_lt_u32_e32 vcc, v1, v0
	s_and_saveexec_b64 s[66:67], vcc
	s_cbranch_execz .LBB0_369
	s_add_i32 s0, s0, -8
	s_xor_b64 s[48:49], exec, -1
	s_sleep 3
	s_branch .LBB0_369

; __device__ __forceinline__ unsigned xb_ld(unsigned* p) { return __hip_atomic_load(p, __ATOMIC_RELAXED, __HIP_MEMORY_SCOPE_AGENT); }
; __device__ __forceinline__ void gbar(unsigned* bar, unsigned n, volatile LAS unsigned* st) {
;     ...
;     } else {
;       while (xb_ld(&bar[XB_XGEN(x)]) <= n) { __builtin_amdgcn_s_sleep(1); if (++sp > (1u << 24)) break; }
;       __builtin_amdgcn_fence(__ATOMIC_ACQUIRE, "agent");
.LBB0_436:
	global_load_dword v2, v[0:1], off sc1
	s_or_b64 s[36:37], s[36:37], exec
	s_waitcnt vmcnt(0) lgkmcnt(0)
	v_cmp_le_u32_e32 vcc, v2, v140
	s_and_saveexec_b64 s[38:39], vcc
	s_cbranch_execz .LBB0_435
	s_cmp_lg_u32 s13, 0
	s_sleep 3
	s_cbranch_scc0 .LBB0_446
	global_load_dword v2, v[0:1], off sc1
	s_mov_b64 s[18:19], -1
	s_waitcnt vmcnt(0) lgkmcnt(0)
	v_cmp_le_u32_e32 vcc, v2, v140
	s_and_saveexec_b64 s[42:43], vcc
	s_cbranch_execz .LBB0_433
	s_sleep 3
	global_load_dword v2, v[0:1], off sc1
	s_waitcnt vmcnt(0) lgkmcnt(0)
	v_cmp_le_u32_e32 vcc, v2, v140
	s_and_saveexec_b64 s[44:45], vcc
	s_cbranch_execz .LBB0_432
	s_sleep 3
	global_load_dword v2, v[0:1], off sc1
	s_waitcnt vmcnt(0) lgkmcnt(0)
	v_cmp_le_u32_e32 vcc, v2, v140
	s_and_saveexec_b64 s[46:47], vcc
	s_cbranch_execz .LBB0_431
	s_sleep 3
	global_load_dword v2, v[0:1], off sc1
	s_waitcnt vmcnt(0) lgkmcnt(0)
	v_cmp_le_u32_e32 vcc, v2, v140
	s_and_saveexec_b64 s[68:69], vcc
	s_cbranch_execz .LBB0_430
	s_sleep 3
	global_load_dword v2, v[0:1], off sc1
	s_waitcnt vmcnt(0) lgkmcnt(0)
	v_cmp_le_u32_e32 vcc, v2, v140
	s_and_saveexec_b64 s[94:95], vcc
	s_cbranch_execz .LBB0_429
	s_sleep 3
	global_load_dword v2, v[0:1], off sc1
	s_mov_b64 s[48:49], -1
	s_waitcnt vmcnt(0) lgkmcnt(0)
	v_cmp_le_u32_e32 vcc, v2, v140
	s_and_saveexec_b64 s[18:19], vcc
	s_cbranch_execz .LBB0_428
	s_sleep 3
	global_load_dword v2, v[0:1], off sc1
	s_waitcnt vmcnt(0) lgkmcnt(0)
	v_cmp_le_u32_e32 vcc, v2, v140
	s_and_saveexec_b64 s[66:67], vcc
	s_cbranch_execz .LBB0_427
	s_add_i32 s13, s13, -8
	s_xor_b64 s[48:49], exec, -1
	s_sleep 3
	s_branch .LBB0_427

; __device__ __forceinline__ unsigned xb_ld(unsigned* p) { return __hip_atomic_load(p, __ATOMIC_RELAXED, __HIP_MEMORY_SCOPE_AGENT); }
; __device__ __forceinline__ void gbar(unsigned* bar, unsigned n, volatile LAS unsigned* st) {
;     ...
;     } else {
;       while (xb_ld(&bar[XB_XGEN(x)]) <= n) { __builtin_amdgcn_s_sleep(1); if (++sp > (1u << 24)) break; }
;       __builtin_amdgcn_fence(__ATOMIC_ACQUIRE, "agent");
.LBB0_501:
	global_load_dword v2, v[0:1], off sc1
	s_or_b64 s[36:37], s[36:37], exec
	s_waitcnt vmcnt(0) lgkmcnt(0)
	v_cmp_le_u32_e32 vcc, v2, v42
	s_and_saveexec_b64 s[38:39], vcc
	s_cbranch_execz .LBB0_500
	s_cmp_lg_u32 s13, 0
	s_sleep 3
	s_cbranch_scc0 .LBB0_511
	global_load_dword v2, v[0:1], off sc1
	s_mov_b64 s[18:19], -1
	s_waitcnt vmcnt(0) lgkmcnt(0)
	v_cmp_le_u32_e32 vcc, v2, v42
	s_and_saveexec_b64 s[40:41], vcc
	s_cbranch_execz .LBB0_498
	s_sleep 3
	global_load_dword v2, v[0:1], off sc1
	s_waitcnt vmcnt(0) lgkmcnt(0)
	v_cmp_le_u32_e32 vcc, v2, v42
	s_and_saveexec_b64 s[42:43], vcc
	s_cbranch_execz .LBB0_497
	s_sleep 3
	global_load_dword v2, v[0:1], off sc1
	s_waitcnt vmcnt(0) lgkmcnt(0)
	v_cmp_le_u32_e32 vcc, v2, v42
	s_and_saveexec_b64 s[44:45], vcc
	s_cbranch_execz .LBB0_496
	s_sleep 3
	global_load_dword v2, v[0:1], off sc1
	s_waitcnt vmcnt(0) lgkmcnt(0)
	v_cmp_le_u32_e32 vcc, v2, v42
	s_and_saveexec_b64 s[46:47], vcc
	s_cbranch_execz .LBB0_495
	s_sleep 3
	global_load_dword v2, v[0:1], off sc1
	s_waitcnt vmcnt(0) lgkmcnt(0)
	v_cmp_le_u32_e32 vcc, v2, v42
	s_and_saveexec_b64 s[68:69], vcc
	s_cbranch_execz .LBB0_494
	s_sleep 3
	global_load_dword v2, v[0:1], off sc1
	s_mov_b64 s[48:49], -1
	s_waitcnt vmcnt(0) lgkmcnt(0)
	v_cmp_le_u32_e32 vcc, v2, v42
	s_and_saveexec_b64 s[18:19], vcc
	s_cbranch_execz .LBB0_493
	s_sleep 3
	global_load_dword v2, v[0:1], off sc1
	s_waitcnt vmcnt(0) lgkmcnt(0)
	v_cmp_le_u32_e32 vcc, v2, v42
	s_and_saveexec_b64 s[66:67], vcc
	s_cbranch_execz .LBB0_492
	s_add_i32 s13, s13, -8
	s_xor_b64 s[48:49], exec, -1
	s_sleep 3
	s_branch .LBB0_492

; __device__ __forceinline__ unsigned xb_ld(unsigned* p) { return __hip_atomic_load(p, __ATOMIC_RELAXED, __HIP_MEMORY_SCOPE_AGENT); }
; __device__ __forceinline__ unsigned xb_add(unsigned* p, unsigned v) { return __hip_atomic_fetch_add(p, v, __ATOMIC_RELAXED, __HIP_MEMORY_SCOPE_AGENT); }
; __device__ __forceinline__ void gbar(unsigned* bar, unsigned n, volatile LAS unsigned* st) {
;     ...
;       xb_add(&bar[XB_TOP], 1u);
;       while (xb_ld(&bar[XB_TOP]) < (n + 1u) * nx) { __builtin_amdgcn_s_sleep(1); if (++sp > (1u << 24)) break; }
;       __builtin_amdgcn_fence(__ATOMIC_ACQUIRE, "agent");
.LBB0_524:
	v_mov_b64_e32 v[2:3], s[6:7]
	global_load_dword v1, v[2:3], off sc1
	s_or_b64 s[36:37], s[36:37], exec
	s_waitcnt vmcnt(0) lgkmcnt(0)
	v_cmp_lt_u32_e32 vcc, v1, v0
	s_and_saveexec_b64 s[38:39], vcc
	s_cbranch_execz .LBB0_523
	s_cmp_lg_u32 s0, 0
	s_sleep 3
	s_cbranch_scc0 .LBB0_534
	v_mov_b64_e32 v[2:3], s[6:7]
	global_load_dword v1, v[2:3], off sc1
	s_mov_b64 s[18:19], -1
	s_waitcnt vmcnt(0) lgkmcnt(0)
	v_cmp_lt_u32_e32 vcc, v1, v0
	s_and_saveexec_b64 s[40:41], vcc
	s_cbranch_execz .LBB0_521
	v_mov_b64_e32 v[2:3], s[6:7]
	s_sleep 3
	global_load_dword v1, v[2:3], off sc1
	s_waitcnt vmcnt(0) lgkmcnt(0)
	v_cmp_lt_u32_e32 vcc, v1, v0
	s_and_saveexec_b64 s[42:43], vcc
	s_cbranch_execz .LBB0_520
	v_mov_b64_e32 v[2:3], s[6:7]
	s_sleep 3
	global_load_dword v1, v[2:3], off sc1
	s_waitcnt vmcnt(0) lgkmcnt(0)
	v_cmp_lt_u32_e32 vcc, v1, v0
	s_and_saveexec_b64 s[44:45], vcc
	s_cbranch_execz .LBB0_519
	v_mov_b64_e32 v[2:3], s[6:7]
	s_sleep 3
	global_load_dword v1, v[2:3], off sc1
	s_waitcnt vmcnt(0) lgkmcnt(0)
	v_cmp_lt_u32_e32 vcc, v1, v0
	s_and_saveexec_b64 s[46:47], vcc
	s_cbranch_execz .LBB0_518
	v_mov_b64_e32 v[2:3], s[6:7]
	s_sleep 3
	global_load_dword v1, v[2:3], off sc1
	s_waitcnt vmcnt(0) lgkmcnt(0)
	v_cmp_lt_u32_e32 vcc, v1, v0
	s_and_saveexec_b64 s[68:69], vcc
	s_cbranch_execz .LBB0_517
	v_mov_b64_e32 v[2:3], s[6:7]
	s_sleep 3
	global_load_dword v1, v[2:3], off sc1
	s_mov_b64 s[48:49], -1
	s_waitcnt vmcnt(0) lgkmcnt(0)
	v_cmp_lt_u32_e32 vcc, v1, v0
	s_and_saveexec_b64 s[18:19], vcc
	s_cbranch_execz .LBB0_516
	v_mov_b64_e32 v[2:3], s[6:7]
	s_sleep 3
	global_load_dword v1, v[2:3], off sc1
	s_waitcnt vmcnt(0) lgkmcnt(0)
	v_cmp_lt_u32_e32 vcc, v1, v0
	s_and_saveexec_b64 s[66:67], vcc
	s_cbranch_execz .LBB0_515
	s_add_i32 s0, s0, -8
	s_xor_b64 s[48:49], exec, -1
	s_sleep 3
	s_branch .LBB0_515

; __device__ __forceinline__ unsigned xb_ld(unsigned* p) { return __hip_atomic_load(p, __ATOMIC_RELAXED, __HIP_MEMORY_SCOPE_AGENT); }
; __device__ __forceinline__ void gbar(unsigned* bar, unsigned n, volatile LAS unsigned* st) {
;     ...
;     } else {
;       while (xb_ld(&bar[XB_XGEN(x)]) <= n) { __builtin_amdgcn_s_sleep(1); if (++sp > (1u << 24)) break; }
;       __builtin_amdgcn_fence(__ATOMIC_ACQUIRE, "agent");
.LBB0_673:
	global_load_dword v2, v[0:1], off sc1
	s_or_b64 s[38:39], s[38:39], exec
	s_waitcnt vmcnt(0) lgkmcnt(0)
	v_cmp_le_u32_e32 vcc, v2, v162
	s_and_saveexec_b64 s[40:41], vcc
	s_cbranch_execz .LBB0_672
	s_cmp_lg_u32 s13, 0
	s_sleep 3
	s_cbranch_scc0 .LBB0_683
	global_load_dword v2, v[0:1], off sc1
	s_mov_b64 s[18:19], -1
	s_waitcnt vmcnt(0) lgkmcnt(0)
	v_cmp_le_u32_e32 vcc, v2, v162
	s_and_saveexec_b64 s[42:43], vcc
	s_cbranch_execz .LBB0_670
	s_sleep 3
	global_load_dword v2, v[0:1], off sc1
	s_waitcnt vmcnt(0) lgkmcnt(0)
	v_cmp_le_u32_e32 vcc, v2, v162
	s_and_saveexec_b64 s[44:45], vcc
	s_cbranch_execz .LBB0_669
	s_sleep 3
	global_load_dword v2, v[0:1], off sc1
	s_waitcnt vmcnt(0) lgkmcnt(0)
	v_cmp_le_u32_e32 vcc, v2, v162
	s_and_saveexec_b64 s[46:47], vcc
	s_cbranch_execz .LBB0_668
	s_sleep 3
	global_load_dword v2, v[0:1], off sc1
	s_waitcnt vmcnt(0) lgkmcnt(0)
	v_cmp_le_u32_e32 vcc, v2, v162
	s_and_saveexec_b64 s[68:69], vcc
	s_cbranch_execz .LBB0_667
	s_sleep 3
	global_load_dword v2, v[0:1], off sc1
	s_waitcnt vmcnt(0) lgkmcnt(0)
	v_cmp_le_u32_e32 vcc, v2, v162
	s_and_saveexec_b64 s[94:95], vcc
	s_cbranch_execz .LBB0_666
	s_sleep 3
	global_load_dword v2, v[0:1], off sc1
	s_mov_b64 s[48:49], -1
	s_waitcnt vmcnt(0) lgkmcnt(0)
	v_cmp_le_u32_e32 vcc, v2, v162
	s_and_saveexec_b64 s[18:19], vcc
	s_cbranch_execz .LBB0_665
	s_sleep 3
	global_load_dword v2, v[0:1], off sc1
	s_waitcnt vmcnt(0) lgkmcnt(0)
	v_cmp_le_u32_e32 vcc, v2, v162
	s_and_saveexec_b64 s[66:67], vcc
	s_cbranch_execz .LBB0_664
	s_add_i32 s13, s13, -8
	s_xor_b64 s[48:49], exec, -1
	s_sleep 3
	s_branch .LBB0_664

; __device__ __forceinline__ unsigned xb_ld(unsigned* p) { return __hip_atomic_load(p, __ATOMIC_RELAXED, __HIP_MEMORY_SCOPE_AGENT); }
; __device__ __forceinline__ unsigned xb_add(unsigned* p, unsigned v) { return __hip_atomic_fetch_add(p, v, __ATOMIC_RELAXED, __HIP_MEMORY_SCOPE_AGENT); }
; __device__ __forceinline__ void gbar(unsigned* bar, unsigned n, volatile LAS unsigned* st) {
;     ...
;       xb_add(&bar[XB_TOP], 1u);
;       while (xb_ld(&bar[XB_TOP]) < (n + 1u) * nx) { __builtin_amdgcn_s_sleep(1); if (++sp > (1u << 24)) break; }
;       __builtin_amdgcn_fence(__ATOMIC_ACQUIRE, "agent");
.LBB0_696:
	v_mov_b64_e32 v[2:3], s[36:37]
	global_load_dword v1, v[2:3], off sc1
	s_or_b64 s[40:41], s[40:41], exec
	s_waitcnt vmcnt(0) lgkmcnt(0)
	v_cmp_lt_u32_e32 vcc, v1, v0
	s_and_saveexec_b64 s[42:43], vcc
	s_cbranch_execz .LBB0_695
	s_cmp_lg_u32 s0, 0
	s_sleep 3
	s_cbranch_scc0 .LBB0_706
	v_mov_b64_e32 v[2:3], s[36:37]
	global_load_dword v1, v[2:3], off sc1
	s_mov_b64 s[18:19], -1
	s_waitcnt vmcnt(0) lgkmcnt(0)
	v_cmp_lt_u32_e32 vcc, v1, v0
	s_and_saveexec_b64 s[44:45], vcc
	s_cbranch_execz .LBB0_693
	v_mov_b64_e32 v[2:3], s[36:37]
	s_sleep 3
	global_load_dword v1, v[2:3], off sc1
	s_waitcnt vmcnt(0) lgkmcnt(0)
	v_cmp_lt_u32_e32 vcc, v1, v0
	s_and_saveexec_b64 s[68:69], vcc
	s_cbranch_execz .LBB0_692
	v_mov_b64_e32 v[2:3], s[36:37]
	s_sleep 3
	global_load_dword v1, v[2:3], off sc1
	s_waitcnt vmcnt(0) lgkmcnt(0)
	v_cmp_lt_u32_e32 vcc, v1, v0
	s_and_saveexec_b64 s[46:47], vcc
	s_cbranch_execz .LBB0_691
	v_mov_b64_e32 v[2:3], s[36:37]
	s_sleep 3
	global_load_dword v1, v[2:3], off sc1
	s_waitcnt vmcnt(0) lgkmcnt(0)
	v_cmp_lt_u32_e32 vcc, v1, v0
	s_and_saveexec_b64 s[94:95], vcc
	s_cbranch_execz .LBB0_690
	v_mov_b64_e32 v[2:3], s[36:37]
	s_sleep 3
	global_load_dword v1, v[2:3], off sc1
	s_waitcnt vmcnt(0) lgkmcnt(0)
	v_cmp_lt_u32_e32 vcc, v1, v0
	s_and_saveexec_b64 s[96:97], vcc
	s_cbranch_execz .LBB0_689
	v_mov_b64_e32 v[2:3], s[36:37]
	s_sleep 3
	global_load_dword v1, v[2:3], off sc1
	s_mov_b64 s[48:49], -1
	s_waitcnt vmcnt(0) lgkmcnt(0)
	v_cmp_lt_u32_e32 vcc, v1, v0
	s_and_saveexec_b64 s[18:19], vcc
	s_cbranch_execz .LBB0_688
	v_mov_b64_e32 v[2:3], s[36:37]
	s_sleep 3
	global_load_dword v1, v[2:3], off sc1
	s_waitcnt vmcnt(0) lgkmcnt(0)
	v_cmp_lt_u32_e32 vcc, v1, v0
	s_and_saveexec_b64 s[66:67], vcc
	s_cbranch_execz .LBB0_687
	s_add_i32 s0, s0, -8
	s_xor_b64 s[48:49], exec, -1
	s_sleep 3
	s_branch .LBB0_687

; __device__ __forceinline__ unsigned xb_ld(unsigned* p) { return __hip_atomic_load(p, __ATOMIC_RELAXED, __HIP_MEMORY_SCOPE_AGENT); }
; __device__ __forceinline__ void gbar(unsigned* bar, unsigned n, volatile LAS unsigned* st) {
;     ...
;     } else {
;       while (xb_ld(&bar[XB_XGEN(x)]) <= n) { __builtin_amdgcn_s_sleep(1); if (++sp > (1u << 24)) break; }
;       __builtin_amdgcn_fence(__ATOMIC_ACQUIRE, "agent");
.LBB0_737:
	global_load_dword v2, v[0:1], off sc1
	s_or_b64 s[38:39], s[38:39], exec
	s_waitcnt vmcnt(0) lgkmcnt(0)
	v_cmp_le_u32_e32 vcc, v2, v181
	s_and_saveexec_b64 s[40:41], vcc
	s_cbranch_execz .LBB0_736
	s_cmp_lg_u32 s13, 0
	s_sleep 3
	s_cbranch_scc0 .LBB0_747
	global_load_dword v2, v[0:1], off sc1
	s_mov_b64 s[18:19], -1
	s_waitcnt vmcnt(0) lgkmcnt(0)
	v_cmp_le_u32_e32 vcc, v2, v181
	s_and_saveexec_b64 s[42:43], vcc
	s_cbranch_execz .LBB0_734
	s_sleep 3
	global_load_dword v2, v[0:1], off sc1
	s_waitcnt vmcnt(0) lgkmcnt(0)
	v_cmp_le_u32_e32 vcc, v2, v181
	s_and_saveexec_b64 s[44:45], vcc
	s_cbranch_execz .LBB0_733
	s_sleep 3
	global_load_dword v2, v[0:1], off sc1
	s_waitcnt vmcnt(0) lgkmcnt(0)
	v_cmp_le_u32_e32 vcc, v2, v181
	s_and_saveexec_b64 s[46:47], vcc
	s_cbranch_execz .LBB0_732
	s_sleep 3
	global_load_dword v2, v[0:1], off sc1
	s_waitcnt vmcnt(0) lgkmcnt(0)
	v_cmp_le_u32_e32 vcc, v2, v181
	s_and_saveexec_b64 s[68:69], vcc
	s_cbranch_execz .LBB0_731
	s_sleep 3
	global_load_dword v2, v[0:1], off sc1
	s_waitcnt vmcnt(0) lgkmcnt(0)
	v_cmp_le_u32_e32 vcc, v2, v181
	s_and_saveexec_b64 s[94:95], vcc
	s_cbranch_execz .LBB0_730
	s_sleep 3
	global_load_dword v2, v[0:1], off sc1
	s_mov_b64 s[48:49], -1
	s_waitcnt vmcnt(0) lgkmcnt(0)
	v_cmp_le_u32_e32 vcc, v2, v181
	s_and_saveexec_b64 s[18:19], vcc
	s_cbranch_execz .LBB0_729
	s_sleep 3
	global_load_dword v2, v[0:1], off sc1
	s_waitcnt vmcnt(0) lgkmcnt(0)
	v_cmp_le_u32_e32 vcc, v2, v181
	s_and_saveexec_b64 s[66:67], vcc
	s_cbranch_execz .LBB0_728
	s_add_i32 s13, s13, -8
	s_xor_b64 s[48:49], exec, -1
	s_sleep 3
	s_branch .LBB0_728

; __device__ __forceinline__ unsigned xb_ld(unsigned* p) { return __hip_atomic_load(p, __ATOMIC_RELAXED, __HIP_MEMORY_SCOPE_AGENT); }
; __device__ __forceinline__ void gbar(unsigned* bar, unsigned n, volatile LAS unsigned* st) {
;     ...
;     } else {
;       while (xb_ld(&bar[XB_XGEN(x)]) <= n) { __builtin_amdgcn_s_sleep(1); if (++sp > (1u << 24)) break; }
;       __builtin_amdgcn_fence(__ATOMIC_ACQUIRE, "agent");
.LBB0_791:
	global_load_dword v2, v[0:1], off sc1
	s_or_b64 s[36:37], s[36:37], exec
	s_waitcnt vmcnt(0) lgkmcnt(0)
	v_cmp_le_u32_e32 vcc, v2, v4
	s_and_saveexec_b64 s[38:39], vcc
	s_cbranch_execz .LBB0_790
	s_cmp_lg_u32 s13, 0
	s_sleep 3
	s_cbranch_scc0 .LBB0_801
	global_load_dword v2, v[0:1], off sc1
	s_mov_b64 s[18:19], -1
	s_waitcnt vmcnt(0) lgkmcnt(0)
	v_cmp_le_u32_e32 vcc, v2, v4
	s_and_saveexec_b64 s[40:41], vcc
	s_cbranch_execz .LBB0_788
	s_sleep 3
	global_load_dword v2, v[0:1], off sc1
	s_waitcnt vmcnt(0) lgkmcnt(0)
	v_cmp_le_u32_e32 vcc, v2, v4
	s_and_saveexec_b64 s[42:43], vcc
	s_cbranch_execz .LBB0_787
	s_sleep 3
	global_load_dword v2, v[0:1], off sc1
	s_waitcnt vmcnt(0) lgkmcnt(0)
	v_cmp_le_u32_e32 vcc, v2, v4
	s_and_saveexec_b64 s[44:45], vcc
	s_cbranch_execz .LBB0_786
	s_sleep 3
	global_load_dword v2, v[0:1], off sc1
	s_waitcnt vmcnt(0) lgkmcnt(0)
	v_cmp_le_u32_e32 vcc, v2, v4
	s_and_saveexec_b64 s[46:47], vcc
	s_cbranch_execz .LBB0_785
	s_sleep 3
	global_load_dword v2, v[0:1], off sc1
	s_waitcnt vmcnt(0) lgkmcnt(0)
	v_cmp_le_u32_e32 vcc, v2, v4
	s_and_saveexec_b64 s[68:69], vcc
	s_cbranch_execz .LBB0_784
	s_sleep 3
	global_load_dword v2, v[0:1], off sc1
	s_mov_b64 s[48:49], -1
	s_waitcnt vmcnt(0) lgkmcnt(0)
	v_cmp_le_u32_e32 vcc, v2, v4
	s_and_saveexec_b64 s[18:19], vcc
	s_cbranch_execz .LBB0_783
	s_sleep 3
	global_load_dword v2, v[0:1], off sc1
	s_waitcnt vmcnt(0) lgkmcnt(0)
	v_cmp_le_u32_e32 vcc, v2, v4
	s_and_saveexec_b64 s[66:67], vcc
	s_cbranch_execz .LBB0_782
	s_add_i32 s13, s13, -8
	s_xor_b64 s[48:49], exec, -1
	s_sleep 3
	s_branch .LBB0_782

; __device__ __forceinline__ unsigned xb_ld(unsigned* p) { return __hip_atomic_load(p, __ATOMIC_RELAXED, __HIP_MEMORY_SCOPE_AGENT); }
; __device__ __forceinline__ void gbar(unsigned* bar, unsigned n, volatile LAS unsigned* st) {
;     ...
;     } else {
;       while (xb_ld(&bar[XB_XGEN(x)]) <= n) { __builtin_amdgcn_s_sleep(1); if (++sp > (1u << 24)) break; }
;       __builtin_amdgcn_fence(__ATOMIC_ACQUIRE, "agent");
.LBB0_880:
	global_load_dword v3, v[0:1], off sc1
	s_or_b64 s[36:37], s[36:37], exec
	s_waitcnt vmcnt(0) lgkmcnt(0)
	v_cmp_le_u32_e32 vcc, v3, v2
	s_and_saveexec_b64 s[38:39], vcc
	s_cbranch_execz .LBB0_879
	s_cmp_lg_u32 s13, 0
	s_sleep 3
	s_cbranch_scc0 .LBB0_890
	global_load_dword v3, v[0:1], off sc1
	s_mov_b64 s[18:19], -1
	s_waitcnt vmcnt(0) lgkmcnt(0)
	v_cmp_le_u32_e32 vcc, v3, v2
	s_and_saveexec_b64 s[40:41], vcc
	s_cbranch_execz .LBB0_877
	s_sleep 3
	global_load_dword v3, v[0:1], off sc1
	s_waitcnt vmcnt(0) lgkmcnt(0)
	v_cmp_le_u32_e32 vcc, v3, v2
	s_and_saveexec_b64 s[42:43], vcc
	s_cbranch_execz .LBB0_876
	s_sleep 3
	global_load_dword v3, v[0:1], off sc1
	s_waitcnt vmcnt(0) lgkmcnt(0)
	v_cmp_le_u32_e32 vcc, v3, v2
	s_and_saveexec_b64 s[44:45], vcc
	s_cbranch_execz .LBB0_875
	s_sleep 3
	global_load_dword v3, v[0:1], off sc1
	s_waitcnt vmcnt(0) lgkmcnt(0)
	v_cmp_le_u32_e32 vcc, v3, v2
	s_and_saveexec_b64 s[46:47], vcc
	s_cbranch_execz .LBB0_874
	s_sleep 3
	global_load_dword v3, v[0:1], off sc1
	s_waitcnt vmcnt(0) lgkmcnt(0)
	v_cmp_le_u32_e32 vcc, v3, v2
	s_and_saveexec_b64 s[68:69], vcc
	s_cbranch_execz .LBB0_873
	s_sleep 3
	global_load_dword v3, v[0:1], off sc1
	s_mov_b64 s[48:49], -1
	s_waitcnt vmcnt(0) lgkmcnt(0)
	v_cmp_le_u32_e32 vcc, v3, v2
	s_and_saveexec_b64 s[18:19], vcc
	s_cbranch_execz .LBB0_872
	s_sleep 3
	global_load_dword v3, v[0:1], off sc1
	s_waitcnt vmcnt(0) lgkmcnt(0)
	v_cmp_le_u32_e32 vcc, v3, v2
	s_and_saveexec_b64 s[66:67], vcc
	s_cbranch_execz .LBB0_871
	s_add_i32 s13, s13, -8
	s_xor_b64 s[48:49], exec, -1
	s_sleep 3
	s_branch .LBB0_871

; __device__ __forceinline__ unsigned xb_ld(unsigned* p) { return __hip_atomic_load(p, __ATOMIC_RELAXED, __HIP_MEMORY_SCOPE_AGENT); }
; __device__ __forceinline__ unsigned xb_add(unsigned* p, unsigned v) { return __hip_atomic_fetch_add(p, v, __ATOMIC_RELAXED, __HIP_MEMORY_SCOPE_AGENT); }
; __device__ __forceinline__ void gbar(unsigned* bar, unsigned n, volatile LAS unsigned* st) {
;     ...
;       xb_add(&bar[XB_TOP], 1u);
;       while (xb_ld(&bar[XB_TOP]) < (n + 1u) * nx) { __builtin_amdgcn_s_sleep(1); if (++sp > (1u << 24)) break; }
;       __builtin_amdgcn_fence(__ATOMIC_ACQUIRE, "agent");
.LBB0_903:
	v_mov_b64_e32 v[2:3], s[8:9]
	global_load_dword v1, v[2:3], off sc1
	s_or_b64 s[38:39], s[38:39], exec
	s_waitcnt vmcnt(0) lgkmcnt(0)
	v_cmp_lt_u32_e32 vcc, v1, v0
	s_and_saveexec_b64 s[40:41], vcc
	s_cbranch_execz .LBB0_902
	s_cmp_lg_u32 s0, 0
	s_sleep 3
	s_cbranch_scc0 .LBB0_913
	v_mov_b64_e32 v[2:3], s[8:9]
	global_load_dword v1, v[2:3], off sc1
	s_mov_b64 s[18:19], -1
	s_waitcnt vmcnt(0) lgkmcnt(0)
	v_cmp_lt_u32_e32 vcc, v1, v0
	s_and_saveexec_b64 s[42:43], vcc
	s_cbranch_execz .LBB0_900
	v_mov_b64_e32 v[2:3], s[8:9]
	s_sleep 3
	global_load_dword v1, v[2:3], off sc1
	s_waitcnt vmcnt(0) lgkmcnt(0)
	v_cmp_lt_u32_e32 vcc, v1, v0
	s_and_saveexec_b64 s[44:45], vcc
	s_cbranch_execz .LBB0_899
	v_mov_b64_e32 v[2:3], s[8:9]
	s_sleep 3
	global_load_dword v1, v[2:3], off sc1
	s_waitcnt vmcnt(0) lgkmcnt(0)
	v_cmp_lt_u32_e32 vcc, v1, v0
	s_and_saveexec_b64 s[46:47], vcc
	s_cbranch_execz .LBB0_898
	v_mov_b64_e32 v[2:3], s[8:9]
	s_sleep 3
	global_load_dword v1, v[2:3], off sc1
	s_waitcnt vmcnt(0) lgkmcnt(0)
	v_cmp_lt_u32_e32 vcc, v1, v0
	s_and_saveexec_b64 s[68:69], vcc
	s_cbranch_execz .LBB0_897
	v_mov_b64_e32 v[2:3], s[8:9]
	s_sleep 3
	global_load_dword v1, v[2:3], off sc1
	s_waitcnt vmcnt(0) lgkmcnt(0)
	v_cmp_lt_u32_e32 vcc, v1, v0
	s_and_saveexec_b64 s[92:93], vcc
	s_cbranch_execz .LBB0_896
	v_mov_b64_e32 v[2:3], s[8:9]
	s_sleep 3
	global_load_dword v1, v[2:3], off sc1
	s_mov_b64 s[48:49], -1
	s_waitcnt vmcnt(0) lgkmcnt(0)
	v_cmp_lt_u32_e32 vcc, v1, v0
	s_and_saveexec_b64 s[18:19], vcc
	s_cbranch_execz .LBB0_895
	v_mov_b64_e32 v[2:3], s[8:9]
	s_sleep 3
	global_load_dword v1, v[2:3], off sc1
	s_waitcnt vmcnt(0) lgkmcnt(0)
	v_cmp_lt_u32_e32 vcc, v1, v0
	s_and_saveexec_b64 s[66:67], vcc
	s_cbranch_execz .LBB0_894
	s_add_i32 s0, s0, -8
	s_xor_b64 s[48:49], exec, -1
	s_sleep 3
	s_branch .LBB0_894

; __device__ __forceinline__ unsigned xb_ld(unsigned* p) { return __hip_atomic_load(p, __ATOMIC_RELAXED, __HIP_MEMORY_SCOPE_AGENT); }
; __device__ __forceinline__ void gbar(unsigned* bar, unsigned n, volatile LAS unsigned* st) {
;     ...
;     } else {
;       while (xb_ld(&bar[XB_XGEN(x)]) <= n) { __builtin_amdgcn_s_sleep(1); if (++sp > (1u << 24)) break; }
;       __builtin_amdgcn_fence(__ATOMIC_ACQUIRE, "agent");
.LBB0_1026:
	global_load_dword v2, v[0:1], off sc1
	s_or_b64 s[36:37], s[36:37], exec
	s_waitcnt vmcnt(0) lgkmcnt(0)
	v_cmp_le_u32_e32 vcc, v2, v159
	s_and_saveexec_b64 s[38:39], vcc
	s_cbranch_execz .LBB0_1025
	s_cmp_lg_u32 s13, 0
	s_sleep 3
	s_cbranch_scc0 .LBB0_1036
	global_load_dword v2, v[0:1], off sc1
	s_mov_b64 s[18:19], -1
	s_waitcnt vmcnt(0) lgkmcnt(0)
	v_cmp_le_u32_e32 vcc, v2, v159
	s_and_saveexec_b64 s[40:41], vcc
	s_cbranch_execz .LBB0_1023
	s_sleep 3
	global_load_dword v2, v[0:1], off sc1
	s_waitcnt vmcnt(0) lgkmcnt(0)
	v_cmp_le_u32_e32 vcc, v2, v159
	s_and_saveexec_b64 s[42:43], vcc
	s_cbranch_execz .LBB0_1022
	s_sleep 3
	global_load_dword v2, v[0:1], off sc1
	s_waitcnt vmcnt(0) lgkmcnt(0)
	v_cmp_le_u32_e32 vcc, v2, v159
	s_and_saveexec_b64 s[44:45], vcc
	s_cbranch_execz .LBB0_1021
	s_sleep 3
	global_load_dword v2, v[0:1], off sc1
	s_waitcnt vmcnt(0) lgkmcnt(0)
	v_cmp_le_u32_e32 vcc, v2, v159
	s_and_saveexec_b64 s[46:47], vcc
	s_cbranch_execz .LBB0_1020
	s_sleep 3
	global_load_dword v2, v[0:1], off sc1
	s_waitcnt vmcnt(0) lgkmcnt(0)
	v_cmp_le_u32_e32 vcc, v2, v159
	s_and_saveexec_b64 s[68:69], vcc
	s_cbranch_execz .LBB0_1019
	s_sleep 3
	global_load_dword v2, v[0:1], off sc1
	s_mov_b64 s[48:49], -1
	s_waitcnt vmcnt(0) lgkmcnt(0)
	v_cmp_le_u32_e32 vcc, v2, v159
	s_and_saveexec_b64 s[18:19], vcc
	s_cbranch_execz .LBB0_1018
	s_sleep 3
	global_load_dword v2, v[0:1], off sc1
	s_waitcnt vmcnt(0) lgkmcnt(0)
	v_cmp_le_u32_e32 vcc, v2, v159
	s_and_saveexec_b64 s[66:67], vcc
	s_cbranch_execz .LBB0_1017
	s_add_i32 s13, s13, -8
	s_xor_b64 s[48:49], exec, -1
	s_sleep 3
	s_branch .LBB0_1017

; __device__ __forceinline__ unsigned xb_ld(unsigned* p) { return __hip_atomic_load(p, __ATOMIC_RELAXED, __HIP_MEMORY_SCOPE_AGENT); }
; __device__ __forceinline__ unsigned xb_add(unsigned* p, unsigned v) { return __hip_atomic_fetch_add(p, v, __ATOMIC_RELAXED, __HIP_MEMORY_SCOPE_AGENT); }
; __device__ __forceinline__ void gbar(unsigned* bar, unsigned n, volatile LAS unsigned* st) {
;     ...
;       xb_add(&bar[XB_TOP], 1u);
;       while (xb_ld(&bar[XB_TOP]) < (n + 1u) * nx) { __builtin_amdgcn_s_sleep(1); if (++sp > (1u << 24)) break; }
;       __builtin_amdgcn_fence(__ATOMIC_ACQUIRE, "agent");
.LBB0_1049:
	v_mov_b64_e32 v[2:3], s[8:9]
	global_load_dword v1, v[2:3], off sc1
	s_or_b64 s[38:39], s[38:39], exec
	s_waitcnt vmcnt(0) lgkmcnt(0)
	v_cmp_lt_u32_e32 vcc, v1, v0
	s_and_saveexec_b64 s[40:41], vcc
	s_cbranch_execz .LBB0_1048
	s_cmp_lg_u32 s0, 0
	s_sleep 3
	s_cbranch_scc0 .LBB0_1059
	v_mov_b64_e32 v[2:3], s[8:9]
	global_load_dword v1, v[2:3], off sc1
	s_mov_b64 s[18:19], -1
	s_waitcnt vmcnt(0) lgkmcnt(0)
	v_cmp_lt_u32_e32 vcc, v1, v0
	s_and_saveexec_b64 s[42:43], vcc
	s_cbranch_execz .LBB0_1046
	v_mov_b64_e32 v[2:3], s[8:9]
	s_sleep 3
	global_load_dword v1, v[2:3], off sc1
	s_waitcnt vmcnt(0) lgkmcnt(0)
	v_cmp_lt_u32_e32 vcc, v1, v0
	s_and_saveexec_b64 s[44:45], vcc
	s_cbranch_execz .LBB0_1045
	v_mov_b64_e32 v[2:3], s[8:9]
	s_sleep 3
	global_load_dword v1, v[2:3], off sc1
	s_waitcnt vmcnt(0) lgkmcnt(0)
	v_cmp_lt_u32_e32 vcc, v1, v0
	s_and_saveexec_b64 s[46:47], vcc
	s_cbranch_execz .LBB0_1044
	v_mov_b64_e32 v[2:3], s[8:9]
	s_sleep 3
	global_load_dword v1, v[2:3], off sc1
	s_waitcnt vmcnt(0) lgkmcnt(0)
	v_cmp_lt_u32_e32 vcc, v1, v0
	s_and_saveexec_b64 s[68:69], vcc
	s_cbranch_execz .LBB0_1043
	v_mov_b64_e32 v[2:3], s[8:9]
	s_sleep 3
	global_load_dword v1, v[2:3], off sc1
	s_waitcnt vmcnt(0) lgkmcnt(0)
	v_cmp_lt_u32_e32 vcc, v1, v0
	s_and_saveexec_b64 s[88:89], vcc
	s_cbranch_execz .LBB0_1042
	v_mov_b64_e32 v[2:3], s[8:9]
	s_sleep 3
	global_load_dword v1, v[2:3], off sc1
	s_mov_b64 s[48:49], -1
	s_waitcnt vmcnt(0) lgkmcnt(0)
	v_cmp_lt_u32_e32 vcc, v1, v0
	s_and_saveexec_b64 s[18:19], vcc
	s_cbranch_execz .LBB0_1041
	v_mov_b64_e32 v[2:3], s[8:9]
	s_sleep 3
	global_load_dword v1, v[2:3], off sc1
	s_waitcnt vmcnt(0) lgkmcnt(0)
	v_cmp_lt_u32_e32 vcc, v1, v0
	s_and_saveexec_b64 s[66:67], vcc
	s_cbranch_execz .LBB0_1040
	s_add_i32 s0, s0, -8
	s_xor_b64 s[48:49], exec, -1
	s_sleep 3
	s_branch .LBB0_1040
